# stack9 + first-segment counted wait relaxed to vmcnt(8+N epilogue stores) on all but the phase's first unit (7 GEMM instances); EpiMix vmcnt(0) only on first unit
# baseline (speedup 1.0000x reference)
; #define PG8_STAGE(bufoff, gbase, voff) do { _Pragma("unroll") for (int _i = 0; _i < 2; ++_i) \
;         __builtin_amdgcn_global_load_lds((const unsigned*)((const char*)(gbase) + (voff)[_i]), (PG8_LAS unsigned*)(lds + (bufoff) + ldsw + _i * 8192), 16, 0, 0); } while (0)
; #define PG8_LDA(dst, b, h) do { _Pragma("unroll") for (int m = 0; m < 4; ++m) _Pragma("unroll") for (int k = 0; k < 2; ++k) dst[m][k] = *(const PG8_LAS bf16x8*)(lds + PG8_SA(b, h) + aoff + m * 2048 + k * 1024); } while (0)
; #define PG8_LDB(dst, b, h) do { _Pragma("unroll") for (int n = 0; n < 2; ++n) _Pragma("unroll") for (int k = 0; k < 2; ++k) dst[n][k] = *(const PG8_LAS bf16x8*)(lds + PG8_SB(b, h) + boff + n * 2048 + k * 1024); } while (0)
; #define PG8_WAIT_V(n) asm volatile("s_waitcnt vmcnt(" #n ")" ::: "memory")
; #define PG8_WAIT_L(n) asm volatile("s_waitcnt lgkmcnt(" #n ")" ::: "memory")
; template <class Epi, class Sched, bool ALIGN_EPI = false, bool SP2 = false, bool ABLK = false, bool BBLK = false>
; __device__ __forceinline__ void gemm_phase(PG8_LAS unsigned char* lds, const Gemm g, const Sched& S, const Epi& E) {
;     ...
;         const char* nA = has_next ? (const char*)g.A + (size_t)nxt.pm * tstepA : cA; const char* nB = has_next ? (const char*)g.Bt + (size_t)nxt.pn * tstepB : cB;
;         for (int t = 0; t < nt; t += 2) {
;             const bool last = (t == nt - 2);
;             const char* a1 = cA + (size_t)(t + 1) * kstepA;
;             const char* a2 = last ? nA : cA + (size_t)(t + 2) * kstepA; const char* b2 = last ? nB : cB + (size_t)(t + 2) * kstepB;
;             const char* a3 = a2 + kstepA; const char* b3 = b2 + kstepB;
;             if (last && has_next) S.a_ready(nxt);
;             if constexpr (SP2) {
;             PG8_LDB(B0, 0, 0); PG8_LDB(B1, 0, 1); PG8_SCHED; PG8_LDA(At, 0, 0); PG8_STAGE(PG8_SA(1, 1), a1 + hstepA, voffA);
;             PG8_WAIT_V(8); PG8_WAIT_L(0); PG8_BAR; PG8_MMA(0, 0, At, B0); PG8_MMA(0, 1, At, B1); PG8_BAR; PG8_SCHED;
;     ...
; #pragma unroll
;         for (int a = 0; a < 2; ++a)
; #pragma unroll
;             for (int b = 0; b < 2; ++b)
; #pragma unroll
;                 for (int m = 0; m < 4; ++m)
; #pragma unroll
;                     for (int n = 0; n < 2; ++n) acc[a][b][m][n] = (f32x4){0.f, 0.f, 0.f, 0.f};
;         cur = nxt; cA = nA; cB = nB; ++ui;
;         if constexpr (ALIGN_EPI) { if (wr == 1) PG8_BAR; }
.LBB0_215:
	s_ashr_i32 s15, s14, 31
	s_lshl_b64 s[18:19], s[14:15], 20
	s_add_u32 s18, s35, s18
	s_addc_u32 s19, s36, s19
	s_and_b64 s[20:21], s[4:5], exec
	s_cselect_b32 s15, s19, s23
	s_cselect_b32 s65, s18, s22
	s_ashr_i32 s13, s12, 31
	s_lshl_b64 s[20:21], s[12:13], 20
	s_add_u32 s20, s37, s20
	s_addc_u32 s21, s40, s21
	s_and_b64 s[26:27], s[4:5], exec
	s_cselect_b32 s13, s21, s25
	s_cselect_b32 s68, s20, s24
	s_add_u32 s22, s22, 0xc000
	s_addc_u32 s23, s23, 0
	s_add_u32 s72, s24, 0x10000
	v_mov_b32_e32 v2, 0
	s_addc_u32 s73, s25, 0
	s_mov_b32 s81, -2
	s_add_u32 s24, s22, 0x4000
	s_addc_u32 s25, s23, 0
	s_cmp_eq_u32 s81, 28
	s_cselect_b32 s28, s65, s24
	s_cselect_b32 s29, s15, s25
	s_cselect_b32 s26, s68, s72
	s_cselect_b32 s27, s13, s73
	s_add_u32 s24, s28, 0x8000
	s_addc_u32 s25, s29, 0
	s_add_i32 s75, 0, 0x10000
	v_add_u32_e32 v142, s75, v145
	s_add_i32 s80, 0, 0x14000
	ds_read_b128 v[148:151], v142
	v_pk_mov_b32 v[2:3], 0, 0
	v_pk_mov_b32 v[4:5], 0, 0
	v_pk_mov_b32 v[6:7], 0, 0
	v_pk_mov_b32 v[8:9], 0, 0
	ds_read_b128 v[152:155], v142 offset:1024
	v_pk_mov_b32 v[10:11], 0, 0
	v_pk_mov_b32 v[12:13], 0, 0
	v_pk_mov_b32 v[14:15], 0, 0
	v_pk_mov_b32 v[16:17], 0, 0
	ds_read_b128 v[156:159], v142 offset:2048
	v_pk_mov_b32 v[18:19], 0, 0
	v_pk_mov_b32 v[20:21], 0, 0
	v_pk_mov_b32 v[22:23], 0, 0
	v_pk_mov_b32 v[24:25], 0, 0
	ds_read_b128 v[160:163], v142 offset:3072
	v_pk_mov_b32 v[26:27], 0, 0
	v_pk_mov_b32 v[28:29], 0, 0
	v_pk_mov_b32 v[30:31], 0, 0
	v_pk_mov_b32 v[32:33], 0, 0
	v_add_u32_e32 v142, s80, v145
	ds_read_b128 v[164:167], v142
	v_pk_mov_b32 v[34:35], 0, 0
	v_pk_mov_b32 v[36:37], 0, 0
	v_pk_mov_b32 v[38:39], 0, 0
	v_pk_mov_b32 v[40:41], 0, 0
	ds_read_b128 v[168:171], v142 offset:1024
	v_pk_mov_b32 v[42:43], 0, 0
	v_pk_mov_b32 v[44:45], 0, 0
	v_pk_mov_b32 v[46:47], 0, 0
	v_pk_mov_b32 v[48:49], 0, 0
	ds_read_b128 v[172:175], v142 offset:2048
	v_pk_mov_b32 v[50:51], 0, 0
	v_pk_mov_b32 v[52:53], 0, 0
	v_pk_mov_b32 v[54:55], 0, 0
	v_pk_mov_b32 v[56:57], 0, 0
	ds_read_b128 v[176:179], v142 offset:3072
	v_pk_mov_b32 v[58:59], 0, 0
	v_pk_mov_b32 v[60:61], 0, 0
	v_pk_mov_b32 v[62:63], 0, 0
	v_pk_mov_b32 v[64:65], 0, 0
	v_lshl_add_u64 v[142:143], s[22:23], 0, v[138:139]
	s_add_i32 m0, s43, 0xc000
	ds_read_b128 v[180:183], v146
	v_pk_mov_b32 v[66:67], 0, 0
	v_pk_mov_b32 v[68:69], 0, 0
	v_pk_mov_b32 v[70:71], 0, 0
	v_pk_mov_b32 v[72:73], 0, 0
	ds_read_b128 v[196:199], v146 offset:1024
	v_pk_mov_b32 v[74:75], 0, 0
	v_pk_mov_b32 v[76:77], 0, 0
	v_pk_mov_b32 v[78:79], 0, 0
	v_pk_mov_b32 v[80:81], 0, 0
	ds_read_b128 v[200:203], v146 offset:2048
	v_pk_mov_b32 v[82:83], 0, 0
	v_pk_mov_b32 v[84:85], 0, 0
	v_pk_mov_b32 v[86:87], 0, 0
	v_pk_mov_b32 v[88:89], 0, 0
	ds_read_b128 v[204:207], v146 offset:3072
	v_pk_mov_b32 v[90:91], 0, 0
	v_pk_mov_b32 v[92:93], 0, 0
	v_pk_mov_b32 v[94:95], 0, 0
	v_pk_mov_b32 v[96:97], 0, 0
	ds_read_b128 v[208:211], v146 offset:4096
	v_pk_mov_b32 v[98:99], 0, 0
	v_pk_mov_b32 v[100:101], 0, 0
	v_pk_mov_b32 v[102:103], 0, 0
	v_pk_mov_b32 v[104:105], 0, 0
	ds_read_b128 v[212:215], v146 offset:5120
	v_pk_mov_b32 v[106:107], 0, 0
	v_pk_mov_b32 v[108:109], 0, 0
	v_pk_mov_b32 v[110:111], 0, 0
	v_pk_mov_b32 v[112:113], 0, 0
	ds_read_b128 v[216:219], v146 offset:6144
	v_pk_mov_b32 v[114:115], 0, 0
	v_pk_mov_b32 v[116:117], 0, 0
	v_pk_mov_b32 v[118:119], 0, 0
	v_pk_mov_b32 v[120:121], 0, 0
	ds_read_b128 v[220:223], v146 offset:7168
	v_pk_mov_b32 v[122:123], 0, 0
	v_pk_mov_b32 v[124:125], 0, 0
	v_pk_mov_b32 v[126:127], 0, 0
	v_pk_mov_b32 v[128:129], 0, 0
	global_load_lds_dwordx4 v[142:143], off
	v_lshl_add_u64 v[142:143], s[22:23], 0, v[140:141]
	s_add_i32 m0, s43, 0xe000
	s_nop 0
	global_load_lds_dwordx4 v[142:143], off
	s_cmp_eq_u32 s61, 1
	s_cbranch_scc1 .Lw8_216
	s_waitcnt vmcnt(16)
	s_branch .Lwd_216
.Lw8_216:
	s_waitcnt vmcnt(8)
.Lwd_216:
	s_waitcnt lgkmcnt(0)
	s_barrier
	s_branch .Lpeel_216

; #define PG8_STAGE(bufoff, gbase, voff) do { _Pragma("unroll") for (int _i = 0; _i < 2; ++_i) \
;         __builtin_amdgcn_global_load_lds((const unsigned*)((const char*)(gbase) + (voff)[_i]), (PG8_LAS unsigned*)(lds + (bufoff) + ldsw + _i * 8192), 16, 0, 0); } while (0)
; #define PG8_LDA(dst, b, h) do { _Pragma("unroll") for (int m = 0; m < 4; ++m) _Pragma("unroll") for (int k = 0; k < 2; ++k) dst[m][k] = *(const PG8_LAS bf16x8*)(lds + PG8_SA(b, h) + aoff + m * 2048 + k * 1024); } while (0)
; #define PG8_LDB(dst, b, h) do { _Pragma("unroll") for (int n = 0; n < 2; ++n) _Pragma("unroll") for (int k = 0; k < 2; ++k) dst[n][k] = *(const PG8_LAS bf16x8*)(lds + PG8_SB(b, h) + boff + n * 2048 + k * 1024); } while (0)
; #define PG8_WAIT_V(n) asm volatile("s_waitcnt vmcnt(" #n ")" ::: "memory")
; #define PG8_WAIT_L(n) asm volatile("s_waitcnt lgkmcnt(" #n ")" ::: "memory")
; template <class Epi, class Sched, bool ALIGN_EPI = false, bool SP2 = false, bool ABLK = false, bool BBLK = false>
; __device__ __forceinline__ void gemm_phase(PG8_LAS unsigned char* lds, const Gemm g, const Sched& S, const Epi& E) {
;     ...
;         const char* nA = has_next ? (const char*)g.A + (size_t)nxt.pm * tstepA : cA; const char* nB = has_next ? (const char*)g.Bt + (size_t)nxt.pn * tstepB : cB;
;         for (int t = 0; t < nt; t += 2) {
;             const bool last = (t == nt - 2);
;             const char* a1 = cA + (size_t)(t + 1) * kstepA;
;             const char* a2 = last ? nA : cA + (size_t)(t + 2) * kstepA; const char* b2 = last ? nB : cB + (size_t)(t + 2) * kstepB;
;             const char* a3 = a2 + kstepA; const char* b3 = b2 + kstepB;
;             if (last && has_next) S.a_ready(nxt);
;             if constexpr (SP2) {
;             PG8_LDB(B0, 0, 0); PG8_LDB(B1, 0, 1); PG8_SCHED; PG8_LDA(At, 0, 0); PG8_STAGE(PG8_SA(1, 1), a1 + hstepA, voffA);
;             PG8_WAIT_V(8); PG8_WAIT_L(0); PG8_BAR; PG8_MMA(0, 0, At, B0); PG8_MMA(0, 1, At, B1); PG8_BAR; PG8_SCHED;
;     ...
; #pragma unroll
;         for (int a = 0; a < 2; ++a)
; #pragma unroll
;             for (int b = 0; b < 2; ++b)
; #pragma unroll
;                 for (int m = 0; m < 4; ++m)
; #pragma unroll
;                     for (int n = 0; n < 2; ++n) acc[a][b][m][n] = (f32x4){0.f, 0.f, 0.f, 0.f};
;         cur = nxt; cA = nA; cB = nB; ++ui;
;         if constexpr (ALIGN_EPI) { if (wr == 1) PG8_BAR; }
.LBB0_593:
	s_ashr_i32 s21, s20, 31
	s_lshl_b64 s[24:25], s[20:21], 20
	s_add_u32 s24, s51, s24
	s_addc_u32 s25, s53, s25
	s_and_b64 s[26:27], s[6:7], exec
	s_cselect_b32 s9, s25, s1
	s_cselect_b32 s16, s24, s0
	s_ashr_i32 s23, s22, 31
	s_lshl_b64 s[26:27], s[22:23], 20
	s_add_u32 s26, s44, s26
	s_addc_u32 s27, s45, s27
	s_and_b64 s[34:35], s[6:7], exec
	s_cselect_b32 s21, s27, s31
	s_cselect_b32 s23, s26, s30
	s_add_u32 s0, s0, 0xc000
	s_addc_u32 s1, s1, 0
	s_add_u32 s29, s30, 0x10000
	v_mov_b32_e32 v2, 0
	s_addc_u32 s40, s31, 0
	s_mov_b32 s41, -2
	v_mov_b32_e32 v3, v2
	v_mov_b32_e32 v4, v2
	v_mov_b32_e32 v5, v2
	v_mov_b32_e32 v6, v2
	v_mov_b32_e32 v7, v2
	v_mov_b32_e32 v8, v2
	v_mov_b32_e32 v9, v2
	s_cmp_eq_u32 s93, 1
	s_cbranch_scc0 .Lw0_594
	s_waitcnt vmcnt(0)
.Lw0_594:
	s_add_u32 s30, s0, 0x4000
	s_addc_u32 s31, s1, 0
	s_cmp_eq_u32 s41, 28
	s_cselect_b32 s36, s16, s30
	s_cselect_b32 s37, s9, s31
	s_cselect_b32 s34, s23, s29
	s_cselect_b32 s35, s21, s40
	s_add_u32 s30, s36, 0x8000
	s_addc_u32 s31, s37, 0
	s_add_i32 s60, 0, 0x10000
	s_add_i32 s75, 0, 0x14000
	v_add_u32_e32 v142, s60, v169
	v_add_u32_e32 v171, s75, v169
	ds_read_b128 v[130:133], v142
	v_pk_mov_b32 v[10:11], 0, 0
	v_pk_mov_b32 v[12:13], 0, 0
	v_pk_mov_b32 v[14:15], 0, 0
	v_pk_mov_b32 v[16:17], 0, 0
	ds_read_b128 v[134:137], v142 offset:1024
	v_pk_mov_b32 v[18:19], 0, 0
	v_pk_mov_b32 v[20:21], 0, 0
	v_pk_mov_b32 v[22:23], 0, 0
	v_pk_mov_b32 v[24:25], 0, 0
	ds_read_b128 v[138:141], v142 offset:2048
	v_pk_mov_b32 v[26:27], 0, 0
	v_pk_mov_b32 v[28:29], 0, 0
	v_pk_mov_b32 v[30:31], 0, 0
	v_pk_mov_b32 v[32:33], 0, 0
	ds_read_b128 v[142:145], v142 offset:3072
	v_pk_mov_b32 v[34:35], 0, 0
	v_pk_mov_b32 v[36:37], 0, 0
	v_pk_mov_b32 v[38:39], 0, 0
	v_pk_mov_b32 v[40:41], 0, 0
	ds_read_b128 v[160:163], v171
	v_pk_mov_b32 v[42:43], 0, 0
	v_pk_mov_b32 v[44:45], 0, 0
	v_pk_mov_b32 v[46:47], 0, 0
	v_pk_mov_b32 v[48:49], 0, 0
	ds_read_b128 v[164:167], v171 offset:1024
	v_pk_mov_b32 v[50:51], 0, 0
	v_pk_mov_b32 v[52:53], 0, 0
	v_pk_mov_b32 v[54:55], 0, 0
	v_pk_mov_b32 v[56:57], 0, 0
	ds_read_b128 v[172:175], v171 offset:2048
	v_pk_mov_b32 v[58:59], 0, 0
	v_pk_mov_b32 v[60:61], 0, 0
	v_pk_mov_b32 v[62:63], 0, 0
	v_pk_mov_b32 v[64:65], 0, 0
	ds_read_b128 v[176:179], v171 offset:3072
	v_pk_mov_b32 v[66:67], 0, 0
	v_pk_mov_b32 v[68:69], 0, 0
	v_pk_mov_b32 v[70:71], 0, 0
	v_pk_mov_b32 v[72:73], 0, 0
	v_lshl_add_u64 v[184:185], s[0:1], 0, v[156:157]
	s_add_i32 m0, s83, 0xc000
	ds_read_b128 v[180:183], v170
	v_pk_mov_b32 v[74:75], 0, 0
	v_pk_mov_b32 v[76:77], 0, 0
	v_pk_mov_b32 v[78:79], 0, 0
	v_pk_mov_b32 v[80:81], 0, 0
	ds_read_b128 v[196:199], v170 offset:1024
	v_pk_mov_b32 v[82:83], 0, 0
	v_pk_mov_b32 v[84:85], 0, 0
	v_pk_mov_b32 v[86:87], 0, 0
	v_pk_mov_b32 v[88:89], 0, 0
	ds_read_b128 v[200:203], v170 offset:2048
	v_pk_mov_b32 v[90:91], 0, 0
	v_pk_mov_b32 v[92:93], 0, 0
	v_pk_mov_b32 v[94:95], 0, 0
	v_pk_mov_b32 v[96:97], 0, 0
	ds_read_b128 v[204:207], v170 offset:3072
	v_pk_mov_b32 v[98:99], 0, 0
	v_pk_mov_b32 v[100:101], 0, 0
	v_pk_mov_b32 v[102:103], 0, 0
	v_pk_mov_b32 v[104:105], 0, 0
	ds_read_b128 v[208:211], v170 offset:4096
	v_pk_mov_b32 v[106:107], 0, 0
	v_pk_mov_b32 v[108:109], 0, 0
	v_pk_mov_b32 v[110:111], 0, 0
	v_pk_mov_b32 v[112:113], 0, 0
	ds_read_b128 v[212:215], v170 offset:5120
	v_pk_mov_b32 v[114:115], 0, 0
	v_pk_mov_b32 v[116:117], 0, 0
	v_pk_mov_b32 v[118:119], 0, 0
	v_pk_mov_b32 v[120:121], 0, 0
	ds_read_b128 v[216:219], v170 offset:6144
	v_pk_mov_b32 v[122:123], 0, 0
	v_pk_mov_b32 v[124:125], 0, 0
	v_pk_mov_b32 v[126:127], 0, 0
	v_pk_mov_b32 v[128:129], 0, 0
	ds_read_b128 v[220:223], v170 offset:7168
	global_load_lds_dwordx4 v[184:185], off
	v_lshl_add_u64 v[184:185], s[0:1], 0, v[158:159]
	s_add_i32 m0, s83, 0xe000
	s_nop 0
	global_load_lds_dwordx4 v[184:185], off
	s_cmp_eq_u32 s93, 1
	s_cbranch_scc1 .Lw8_594
	s_waitcnt vmcnt(28)
	s_branch .Lwd_594

; #define PG8_STAGE(bufoff, gbase, voff) do { _Pragma("unroll") for (int _i = 0; _i < 2; ++_i) \
;         __builtin_amdgcn_global_load_lds((const unsigned*)((const char*)(gbase) + (voff)[_i]), (PG8_LAS unsigned*)(lds + (bufoff) + ldsw + _i * 8192), 16, 0, 0); } while (0)
; #define PG8_LDA(dst, b, h) do { _Pragma("unroll") for (int m = 0; m < 4; ++m) _Pragma("unroll") for (int k = 0; k < 2; ++k) dst[m][k] = *(const PG8_LAS bf16x8*)(lds + PG8_SA(b, h) + aoff + m * 2048 + k * 1024); } while (0)
; #define PG8_LDB(dst, b, h) do { _Pragma("unroll") for (int n = 0; n < 2; ++n) _Pragma("unroll") for (int k = 0; k < 2; ++k) dst[n][k] = *(const PG8_LAS bf16x8*)(lds + PG8_SB(b, h) + boff + n * 2048 + k * 1024); } while (0)
; #define PG8_WAIT_V(n) asm volatile("s_waitcnt vmcnt(" #n ")" ::: "memory")
; #define PG8_WAIT_L(n) asm volatile("s_waitcnt lgkmcnt(" #n ")" ::: "memory")
; template <class Epi, class Sched, bool ALIGN_EPI = false, bool SP2 = false, bool ABLK = false, bool BBLK = false>
; __device__ __forceinline__ void gemm_phase(PG8_LAS unsigned char* lds, const Gemm g, const Sched& S, const Epi& E) {
;     ...
;         const char* nA = has_next ? (const char*)g.A + (size_t)nxt.pm * tstepA : cA; const char* nB = has_next ? (const char*)g.Bt + (size_t)nxt.pn * tstepB : cB;
;         for (int t = 0; t < nt; t += 2) {
;             const bool last = (t == nt - 2);
;             const char* a1 = cA + (size_t)(t + 1) * kstepA;
;             const char* a2 = last ? nA : cA + (size_t)(t + 2) * kstepA; const char* b2 = last ? nB : cB + (size_t)(t + 2) * kstepB;
;             const char* a3 = a2 + kstepA; const char* b3 = b2 + kstepB;
;             if (last && has_next) S.a_ready(nxt);
;             if constexpr (SP2) {
;             PG8_LDB(B0, 0, 0); PG8_LDB(B1, 0, 1); PG8_SCHED; PG8_LDA(At, 0, 0); PG8_STAGE(PG8_SA(1, 1), a1 + hstepA, voffA);
;             PG8_WAIT_V(8); PG8_WAIT_L(0); PG8_BAR; PG8_MMA(0, 0, At, B0); PG8_MMA(0, 1, At, B1); PG8_BAR; PG8_SCHED;
;     ...
; #pragma unroll
;         for (int a = 0; a < 2; ++a)
; #pragma unroll
;             for (int b = 0; b < 2; ++b)
; #pragma unroll
;                 for (int m = 0; m < 4; ++m)
; #pragma unroll
;                     for (int n = 0; n < 2; ++n) acc[a][b][m][n] = (f32x4){0.f, 0.f, 0.f, 0.f};
;         cur = nxt; cA = nA; cB = nB; ++ui;
;         if constexpr (ALIGN_EPI) { if (wr == 1) PG8_BAR; }
.LBB0_657:
	s_ashr_i32 s13, s12, 31
	s_lshl_b64 s[14:15], s[12:13], 20
	s_add_u32 s14, s31, s14
	s_addc_u32 s15, s33, s15
	s_and_b64 s[18:19], s[6:7], exec
	s_cselect_b32 s13, s15, s23
	s_cselect_b32 s61, s14, s22
	s_ashr_i32 s1, s0, 31
	s_lshl_b64 s[18:19], s[0:1], 20
	s_add_u32 s18, s51, s18
	s_addc_u32 s19, s53, s19
	s_and_b64 s[26:27], s[6:7], exec
	s_cselect_b32 s1, s19, s25
	s_cselect_b32 s65, s18, s24
	s_add_u32 s22, s22, 0xc000
	s_addc_u32 s23, s23, 0
	s_add_u32 s68, s24, 0x10000
	v_mov_b32_e32 v2, 0
	s_addc_u32 s72, s25, 0
	s_mov_b32 s73, -2
	s_add_u32 s24, s22, 0x4000
	s_addc_u32 s25, s23, 0
	s_cmp_eq_u32 s73, 28
	s_cselect_b32 s28, s61, s24
	s_cselect_b32 s29, s13, s25
	s_cselect_b32 s26, s65, s68
	s_cselect_b32 s27, s1, s72
	s_add_u32 s24, s28, 0x8000
	s_addc_u32 s25, s29, 0
	s_add_i32 s75, 0, 0x10000
	s_add_i32 s82, 0, 0x14000
	v_add_u32_e32 v158, s75, v147
	v_add_u32_e32 v174, s82, v147
	ds_read_b128 v[142:145], v158
	v_pk_mov_b32 v[2:3], 0, 0
	v_pk_mov_b32 v[4:5], 0, 0
	v_pk_mov_b32 v[6:7], 0, 0
	v_pk_mov_b32 v[8:9], 0, 0
	ds_read_b128 v[150:153], v158 offset:1024
	v_pk_mov_b32 v[10:11], 0, 0
	v_pk_mov_b32 v[12:13], 0, 0
	v_pk_mov_b32 v[14:15], 0, 0
	v_pk_mov_b32 v[16:17], 0, 0
	ds_read_b128 v[154:157], v158 offset:2048
	v_pk_mov_b32 v[18:19], 0, 0
	v_pk_mov_b32 v[20:21], 0, 0
	v_pk_mov_b32 v[22:23], 0, 0
	v_pk_mov_b32 v[24:25], 0, 0
	ds_read_b128 v[158:161], v158 offset:3072
	v_pk_mov_b32 v[26:27], 0, 0
	v_pk_mov_b32 v[28:29], 0, 0
	v_pk_mov_b32 v[30:31], 0, 0
	v_pk_mov_b32 v[32:33], 0, 0
	ds_read_b128 v[162:165], v174
	v_pk_mov_b32 v[34:35], 0, 0
	v_pk_mov_b32 v[36:37], 0, 0
	v_pk_mov_b32 v[38:39], 0, 0
	v_pk_mov_b32 v[40:41], 0, 0
	ds_read_b128 v[166:169], v174 offset:1024
	v_pk_mov_b32 v[42:43], 0, 0
	v_pk_mov_b32 v[44:45], 0, 0
	v_pk_mov_b32 v[46:47], 0, 0
	v_pk_mov_b32 v[48:49], 0, 0
	ds_read_b128 v[170:173], v174 offset:2048
	v_pk_mov_b32 v[50:51], 0, 0
	v_pk_mov_b32 v[52:53], 0, 0
	v_pk_mov_b32 v[54:55], 0, 0
	v_pk_mov_b32 v[56:57], 0, 0
	ds_read_b128 v[174:177], v174 offset:3072
	v_pk_mov_b32 v[58:59], 0, 0
	v_pk_mov_b32 v[60:61], 0, 0
	v_pk_mov_b32 v[62:63], 0, 0
	v_pk_mov_b32 v[64:65], 0, 0
	v_lshl_add_u64 v[220:221], s[22:23], 0, v[138:139]
	s_add_i32 m0, s40, 0xc000
	ds_read_b128 v[178:181], v149
	v_pk_mov_b32 v[66:67], 0, 0
	v_pk_mov_b32 v[68:69], 0, 0
	v_pk_mov_b32 v[70:71], 0, 0
	v_pk_mov_b32 v[72:73], 0, 0
	ds_read_b128 v[182:185], v149 offset:1024
	v_pk_mov_b32 v[74:75], 0, 0
	v_pk_mov_b32 v[76:77], 0, 0
	v_pk_mov_b32 v[78:79], 0, 0
	v_pk_mov_b32 v[80:81], 0, 0
	ds_read_b128 v[196:199], v149 offset:2048
	v_pk_mov_b32 v[82:83], 0, 0
	v_pk_mov_b32 v[84:85], 0, 0
	v_pk_mov_b32 v[86:87], 0, 0
	v_pk_mov_b32 v[88:89], 0, 0
	ds_read_b128 v[200:203], v149 offset:3072
	v_pk_mov_b32 v[90:91], 0, 0
	v_pk_mov_b32 v[92:93], 0, 0
	v_pk_mov_b32 v[94:95], 0, 0
	v_pk_mov_b32 v[96:97], 0, 0
	ds_read_b128 v[204:207], v149 offset:4096
	v_pk_mov_b32 v[98:99], 0, 0
	v_pk_mov_b32 v[100:101], 0, 0
	v_pk_mov_b32 v[102:103], 0, 0
	v_pk_mov_b32 v[104:105], 0, 0
	ds_read_b128 v[208:211], v149 offset:5120
	v_pk_mov_b32 v[106:107], 0, 0
	v_pk_mov_b32 v[108:109], 0, 0
	v_pk_mov_b32 v[110:111], 0, 0
	v_pk_mov_b32 v[112:113], 0, 0
	ds_read_b128 v[212:215], v149 offset:6144
	v_pk_mov_b32 v[114:115], 0, 0
	v_pk_mov_b32 v[116:117], 0, 0
	v_pk_mov_b32 v[118:119], 0, 0
	v_pk_mov_b32 v[120:121], 0, 0
	ds_read_b128 v[216:219], v149 offset:7168
	v_pk_mov_b32 v[122:123], 0, 0
	v_pk_mov_b32 v[124:125], 0, 0
	v_pk_mov_b32 v[126:127], 0, 0
	v_pk_mov_b32 v[128:129], 0, 0
	global_load_lds_dwordx4 v[220:221], off
	v_lshl_add_u64 v[220:221], s[22:23], 0, v[140:141]
	s_add_i32 m0, s40, 0xe000
	s_nop 0
	global_load_lds_dwordx4 v[220:221], off
	s_cmp_eq_u32 s60, 1
	s_cbranch_scc1 .Lw8_658
	s_waitcnt vmcnt(24)
	s_branch .Lwd_658

; #define PG8_STAGE(bufoff, gbase, voff) do { _Pragma("unroll") for (int _i = 0; _i < 2; ++_i) \
;         __builtin_amdgcn_global_load_lds((const unsigned*)((const char*)(gbase) + (voff)[_i]), (PG8_LAS unsigned*)(lds + (bufoff) + ldsw + _i * 8192), 16, 0, 0); } while (0)
; #define PG8_LDA(dst, b, h) do { _Pragma("unroll") for (int m = 0; m < 4; ++m) _Pragma("unroll") for (int k = 0; k < 2; ++k) dst[m][k] = *(const PG8_LAS bf16x8*)(lds + PG8_SA(b, h) + aoff + m * 2048 + k * 1024); } while (0)
; #define PG8_LDB(dst, b, h) do { _Pragma("unroll") for (int n = 0; n < 2; ++n) _Pragma("unroll") for (int k = 0; k < 2; ++k) dst[n][k] = *(const PG8_LAS bf16x8*)(lds + PG8_SB(b, h) + boff + n * 2048 + k * 1024); } while (0)
; #define PG8_WAIT_V(n) asm volatile("s_waitcnt vmcnt(" #n ")" ::: "memory")
; #define PG8_WAIT_L(n) asm volatile("s_waitcnt lgkmcnt(" #n ")" ::: "memory")
; template <class Epi, class Sched, bool ALIGN_EPI = false, bool SP2 = false, bool ABLK = false, bool BBLK = false>
; __device__ __forceinline__ void gemm_phase(PG8_LAS unsigned char* lds, const Gemm g, const Sched& S, const Epi& E) {
;     ...
;         const char* nA = has_next ? (const char*)g.A + (size_t)nxt.pm * tstepA : cA; const char* nB = has_next ? (const char*)g.Bt + (size_t)nxt.pn * tstepB : cB;
;         for (int t = 0; t < nt; t += 2) {
;             const bool last = (t == nt - 2);
;             const char* a1 = cA + (size_t)(t + 1) * kstepA;
;             const char* a2 = last ? nA : cA + (size_t)(t + 2) * kstepA; const char* b2 = last ? nB : cB + (size_t)(t + 2) * kstepB;
;             const char* a3 = a2 + kstepA; const char* b3 = b2 + kstepB;
;             if (last && has_next) S.a_ready(nxt);
;             if constexpr (SP2) {
;             PG8_LDB(B0, 0, 0); PG8_LDB(B1, 0, 1); PG8_SCHED; PG8_LDA(At, 0, 0); PG8_STAGE(PG8_SA(1, 1), a1 + hstepA, voffA);
;             PG8_WAIT_V(8); PG8_WAIT_L(0); PG8_BAR; PG8_MMA(0, 0, At, B0); PG8_MMA(0, 1, At, B1); PG8_BAR; PG8_SCHED;
;     ...
; #pragma unroll
;         for (int a = 0; a < 2; ++a)
; #pragma unroll
;             for (int b = 0; b < 2; ++b)
; #pragma unroll
;                 for (int m = 0; m < 4; ++m)
; #pragma unroll
;                     for (int n = 0; n < 2; ++n) acc[a][b][m][n] = (f32x4){0.f, 0.f, 0.f, 0.f};
;         cur = nxt; cA = nA; cB = nB; ++ui;
;         if constexpr (ALIGN_EPI) { if (wr == 1) PG8_BAR; }
.LBB0_765:
	s_ashr_i32 s15, s14, 31
	s_lshl_b64 s[18:19], s[14:15], 20
	s_add_u32 s18, s33, s18
	s_addc_u32 s19, s34, s19
	s_and_b64 s[20:21], s[6:7], exec
	s_cselect_b32 s1, s19, s25
	s_cselect_b32 s11, s18, s24
	s_ashr_i32 s13, s12, 31
	s_lshl_b64 s[20:21], s[12:13], 20
	s_add_u32 s20, s35, s20
	s_addc_u32 s21, s36, s21
	s_and_b64 s[28:29], s[6:7], exec
	s_cselect_b32 s13, s21, s27
	s_cselect_b32 s15, s20, s26
	s_add_u32 s24, s24, 0x80080
	s_addc_u32 s25, s25, 0
	s_add_u32 s23, s26, 0x100
	v_mov_b32_e32 v2, 0
	s_addc_u32 s65, s27, 0
	s_mov_b32 s68, -2
	s_add_u32 s26, s24, 0xfff80080
	s_addc_u32 s27, s25, -1
	s_add_i32 s72, 0, 0x10000
	s_cmp_eq_u32 s68, 28
	s_cselect_b32 s29, s1, s27
	s_cselect_b32 s28, s11, s26
	v_add_u32_e32 v142, s72, v145
	s_cselect_b32 s27, s13, s65
	s_cselect_b32 s26, s15, s23
	s_add_i32 s75, 0, 0x14000
	ds_read_b128 v[148:151], v142
	v_pk_mov_b32 v[2:3], 0, 0
	v_pk_mov_b32 v[4:5], 0, 0
	v_pk_mov_b32 v[6:7], 0, 0
	v_pk_mov_b32 v[8:9], 0, 0
	ds_read_b128 v[152:155], v142 offset:1024
	v_pk_mov_b32 v[10:11], 0, 0
	v_pk_mov_b32 v[12:13], 0, 0
	v_pk_mov_b32 v[14:15], 0, 0
	v_pk_mov_b32 v[16:17], 0, 0
	ds_read_b128 v[156:159], v142 offset:2048
	v_pk_mov_b32 v[18:19], 0, 0
	v_pk_mov_b32 v[20:21], 0, 0
	v_pk_mov_b32 v[22:23], 0, 0
	v_pk_mov_b32 v[24:25], 0, 0
	ds_read_b128 v[160:163], v142 offset:3072
	v_pk_mov_b32 v[26:27], 0, 0
	v_pk_mov_b32 v[28:29], 0, 0
	v_pk_mov_b32 v[30:31], 0, 0
	v_pk_mov_b32 v[32:33], 0, 0
	v_add_u32_e32 v142, s75, v145
	ds_read_b128 v[164:167], v142
	v_pk_mov_b32 v[34:35], 0, 0
	v_pk_mov_b32 v[36:37], 0, 0
	v_pk_mov_b32 v[38:39], 0, 0
	v_pk_mov_b32 v[40:41], 0, 0
	ds_read_b128 v[168:171], v142 offset:1024
	v_pk_mov_b32 v[42:43], 0, 0
	v_pk_mov_b32 v[44:45], 0, 0
	v_pk_mov_b32 v[46:47], 0, 0
	v_pk_mov_b32 v[48:49], 0, 0
	ds_read_b128 v[172:175], v142 offset:2048
	v_pk_mov_b32 v[50:51], 0, 0
	v_pk_mov_b32 v[52:53], 0, 0
	v_pk_mov_b32 v[54:55], 0, 0
	v_pk_mov_b32 v[56:57], 0, 0
	ds_read_b128 v[176:179], v142 offset:3072
	v_pk_mov_b32 v[58:59], 0, 0
	v_pk_mov_b32 v[60:61], 0, 0
	v_pk_mov_b32 v[62:63], 0, 0
	v_pk_mov_b32 v[64:65], 0, 0
	v_lshl_add_u64 v[142:143], s[24:25], 0, v[138:139]
	s_add_i32 m0, s45, 0xc000
	ds_read_b128 v[180:183], v146
	v_pk_mov_b32 v[66:67], 0, 0
	v_pk_mov_b32 v[68:69], 0, 0
	v_pk_mov_b32 v[70:71], 0, 0
	v_pk_mov_b32 v[72:73], 0, 0
	ds_read_b128 v[196:199], v146 offset:1024
	v_pk_mov_b32 v[74:75], 0, 0
	v_pk_mov_b32 v[76:77], 0, 0
	v_pk_mov_b32 v[78:79], 0, 0
	v_pk_mov_b32 v[80:81], 0, 0
	ds_read_b128 v[200:203], v146 offset:2048
	v_pk_mov_b32 v[82:83], 0, 0
	v_pk_mov_b32 v[84:85], 0, 0
	v_pk_mov_b32 v[86:87], 0, 0
	v_pk_mov_b32 v[88:89], 0, 0
	ds_read_b128 v[204:207], v146 offset:3072
	v_pk_mov_b32 v[90:91], 0, 0
	v_pk_mov_b32 v[92:93], 0, 0
	v_pk_mov_b32 v[94:95], 0, 0
	v_pk_mov_b32 v[96:97], 0, 0
	ds_read_b128 v[208:211], v146 offset:4096
	v_pk_mov_b32 v[98:99], 0, 0
	v_pk_mov_b32 v[100:101], 0, 0
	v_pk_mov_b32 v[102:103], 0, 0
	v_pk_mov_b32 v[104:105], 0, 0
	ds_read_b128 v[212:215], v146 offset:5120
	v_pk_mov_b32 v[106:107], 0, 0
	v_pk_mov_b32 v[108:109], 0, 0
	v_pk_mov_b32 v[110:111], 0, 0
	v_pk_mov_b32 v[112:113], 0, 0
	ds_read_b128 v[216:219], v146 offset:6144
	v_pk_mov_b32 v[114:115], 0, 0
	v_pk_mov_b32 v[116:117], 0, 0
	v_pk_mov_b32 v[118:119], 0, 0
	v_pk_mov_b32 v[120:121], 0, 0
	ds_read_b128 v[220:223], v146 offset:7168
	v_pk_mov_b32 v[122:123], 0, 0
	v_pk_mov_b32 v[124:125], 0, 0
	v_pk_mov_b32 v[126:127], 0, 0
	v_pk_mov_b32 v[128:129], 0, 0
	global_load_lds_dwordx4 v[142:143], off
	v_lshl_add_u64 v[142:143], s[24:25], 0, v[140:141]
	s_add_i32 m0, s45, 0xe000
	s_nop 0
	global_load_lds_dwordx4 v[142:143], off
	s_cmp_eq_u32 s61, 1
	s_cbranch_scc1 .Lw8_766
	s_waitcnt vmcnt(24)
	s_branch .Lwd_766

; #define PG8_STAGE(bufoff, gbase, voff) do { _Pragma("unroll") for (int _i = 0; _i < 2; ++_i) \
;         __builtin_amdgcn_global_load_lds((const unsigned*)((const char*)(gbase) + (voff)[_i]), (PG8_LAS unsigned*)(lds + (bufoff) + ldsw + _i * 8192), 16, 0, 0); } while (0)
; #define PG8_LDA(dst, b, h) do { _Pragma("unroll") for (int m = 0; m < 4; ++m) _Pragma("unroll") for (int k = 0; k < 2; ++k) dst[m][k] = *(const PG8_LAS bf16x8*)(lds + PG8_SA(b, h) + aoff + m * 2048 + k * 1024); } while (0)
; #define PG8_LDB(dst, b, h) do { _Pragma("unroll") for (int n = 0; n < 2; ++n) _Pragma("unroll") for (int k = 0; k < 2; ++k) dst[n][k] = *(const PG8_LAS bf16x8*)(lds + PG8_SB(b, h) + boff + n * 2048 + k * 1024); } while (0)
; #define PG8_WAIT_V(n) asm volatile("s_waitcnt vmcnt(" #n ")" ::: "memory")
; #define PG8_WAIT_L(n) asm volatile("s_waitcnt lgkmcnt(" #n ")" ::: "memory")
; template <class Epi, class Sched, bool ALIGN_EPI = false, bool SP2 = false, bool ABLK = false, bool BBLK = false>
; __device__ __forceinline__ void gemm_phase(PG8_LAS unsigned char* lds, const Gemm g, const Sched& S, const Epi& E) {
;     ...
;         const char* nA = has_next ? (const char*)g.A + (size_t)nxt.pm * tstepA : cA; const char* nB = has_next ? (const char*)g.Bt + (size_t)nxt.pn * tstepB : cB;
;         for (int t = 0; t < nt; t += 2) {
;             const bool last = (t == nt - 2);
;             const char* a1 = cA + (size_t)(t + 1) * kstepA;
;             const char* a2 = last ? nA : cA + (size_t)(t + 2) * kstepA; const char* b2 = last ? nB : cB + (size_t)(t + 2) * kstepB;
;             const char* a3 = a2 + kstepA; const char* b3 = b2 + kstepB;
;             if (last && has_next) S.a_ready(nxt);
;             if constexpr (SP2) {
;             PG8_LDB(B0, 0, 0); PG8_LDB(B1, 0, 1); PG8_SCHED; PG8_LDA(At, 0, 0); PG8_STAGE(PG8_SA(1, 1), a1 + hstepA, voffA);
;             PG8_WAIT_V(8); PG8_WAIT_L(0); PG8_BAR; PG8_MMA(0, 0, At, B0); PG8_MMA(0, 1, At, B1); PG8_BAR; PG8_SCHED;
;     ...
; #pragma unroll
;         for (int a = 0; a < 2; ++a)
; #pragma unroll
;             for (int b = 0; b < 2; ++b)
; #pragma unroll
;                 for (int m = 0; m < 4; ++m)
; #pragma unroll
;                     for (int n = 0; n < 2; ++n) acc[a][b][m][n] = (f32x4){0.f, 0.f, 0.f, 0.f};
;         cur = nxt; cA = nA; cB = nB; ++ui;
;         if constexpr (ALIGN_EPI) { if (wr == 1) PG8_BAR; }
.LBB0_789:
	s_ashr_i32 s15, s14, 31
	s_lshl_b64 s[18:19], s[14:15], 20
	s_add_u32 s18, s36, s18
	s_addc_u32 s19, s37, s19
	s_and_b64 s[20:21], s[6:7], exec
	s_cselect_b32 s1, s19, s25
	s_cselect_b32 s11, s18, s24
	s_ashr_i32 s13, s12, 31
	s_lshl_b64 s[20:21], s[12:13], 20
	s_add_u32 s20, s44, s20
	s_addc_u32 s21, s45, s21
	s_and_b64 s[28:29], s[6:7], exec
	s_cselect_b32 s13, s21, s27
	s_cselect_b32 s15, s20, s26
	s_add_u32 s24, s24, 0x80080
	s_addc_u32 s25, s25, 0
	s_add_u32 s23, s26, 0x100
	v_mov_b32_e32 v2, 0
	s_addc_u32 s73, s27, 0
	s_mov_b32 s81, -2
	s_add_u32 s26, s24, 0xfff80080
	s_addc_u32 s27, s25, -1
	s_add_i32 s51, 0, 0x10000
	s_cmp_eq_u32 s81, 28
	s_cselect_b32 s29, s1, s27
	s_cselect_b32 s28, s11, s26
	v_add_u32_e32 v142, s51, v145
	s_cselect_b32 s27, s13, s73
	s_cselect_b32 s26, s15, s23
	s_add_i32 s75, 0, 0x14000
	ds_read_b128 v[148:151], v142
	v_pk_mov_b32 v[2:3], 0, 0
	v_pk_mov_b32 v[4:5], 0, 0
	v_pk_mov_b32 v[6:7], 0, 0
	v_pk_mov_b32 v[8:9], 0, 0
	ds_read_b128 v[152:155], v142 offset:1024
	v_pk_mov_b32 v[10:11], 0, 0
	v_pk_mov_b32 v[12:13], 0, 0
	v_pk_mov_b32 v[14:15], 0, 0
	v_pk_mov_b32 v[16:17], 0, 0
	ds_read_b128 v[156:159], v142 offset:2048
	v_pk_mov_b32 v[18:19], 0, 0
	v_pk_mov_b32 v[20:21], 0, 0
	v_pk_mov_b32 v[22:23], 0, 0
	v_pk_mov_b32 v[24:25], 0, 0
	ds_read_b128 v[160:163], v142 offset:3072
	v_pk_mov_b32 v[26:27], 0, 0
	v_pk_mov_b32 v[28:29], 0, 0
	v_pk_mov_b32 v[30:31], 0, 0
	v_pk_mov_b32 v[32:33], 0, 0
	v_add_u32_e32 v142, s75, v145
	ds_read_b128 v[164:167], v142
	v_pk_mov_b32 v[34:35], 0, 0
	v_pk_mov_b32 v[36:37], 0, 0
	v_pk_mov_b32 v[38:39], 0, 0
	v_pk_mov_b32 v[40:41], 0, 0
	ds_read_b128 v[168:171], v142 offset:1024
	v_pk_mov_b32 v[42:43], 0, 0
	v_pk_mov_b32 v[44:45], 0, 0
	v_pk_mov_b32 v[46:47], 0, 0
	v_pk_mov_b32 v[48:49], 0, 0
	ds_read_b128 v[172:175], v142 offset:2048
	v_pk_mov_b32 v[50:51], 0, 0
	v_pk_mov_b32 v[52:53], 0, 0
	v_pk_mov_b32 v[54:55], 0, 0
	v_pk_mov_b32 v[56:57], 0, 0
	ds_read_b128 v[176:179], v142 offset:3072
	v_pk_mov_b32 v[58:59], 0, 0
	v_pk_mov_b32 v[60:61], 0, 0
	v_pk_mov_b32 v[62:63], 0, 0
	v_pk_mov_b32 v[64:65], 0, 0
	v_lshl_add_u64 v[142:143], s[24:25], 0, v[138:139]
	s_add_i32 m0, s46, 0xc000
	ds_read_b128 v[180:183], v146
	v_pk_mov_b32 v[66:67], 0, 0
	v_pk_mov_b32 v[68:69], 0, 0
	v_pk_mov_b32 v[70:71], 0, 0
	v_pk_mov_b32 v[72:73], 0, 0
	ds_read_b128 v[196:199], v146 offset:1024
	v_pk_mov_b32 v[74:75], 0, 0
	v_pk_mov_b32 v[76:77], 0, 0
	v_pk_mov_b32 v[78:79], 0, 0
	v_pk_mov_b32 v[80:81], 0, 0
	ds_read_b128 v[200:203], v146 offset:2048
	v_pk_mov_b32 v[82:83], 0, 0
	v_pk_mov_b32 v[84:85], 0, 0
	v_pk_mov_b32 v[86:87], 0, 0
	v_pk_mov_b32 v[88:89], 0, 0
	ds_read_b128 v[204:207], v146 offset:3072
	v_pk_mov_b32 v[90:91], 0, 0
	v_pk_mov_b32 v[92:93], 0, 0
	v_pk_mov_b32 v[94:95], 0, 0
	v_pk_mov_b32 v[96:97], 0, 0
	ds_read_b128 v[208:211], v146 offset:4096
	v_pk_mov_b32 v[98:99], 0, 0
	v_pk_mov_b32 v[100:101], 0, 0
	v_pk_mov_b32 v[102:103], 0, 0
	v_pk_mov_b32 v[104:105], 0, 0
	ds_read_b128 v[212:215], v146 offset:5120
	v_pk_mov_b32 v[106:107], 0, 0
	v_pk_mov_b32 v[108:109], 0, 0
	v_pk_mov_b32 v[110:111], 0, 0
	v_pk_mov_b32 v[112:113], 0, 0
	ds_read_b128 v[216:219], v146 offset:6144
	v_pk_mov_b32 v[114:115], 0, 0
	v_pk_mov_b32 v[116:117], 0, 0
	v_pk_mov_b32 v[118:119], 0, 0
	v_pk_mov_b32 v[120:121], 0, 0
	ds_read_b128 v[220:223], v146 offset:7168
	v_pk_mov_b32 v[122:123], 0, 0
	v_pk_mov_b32 v[124:125], 0, 0
	v_pk_mov_b32 v[126:127], 0, 0
	v_pk_mov_b32 v[128:129], 0, 0
	global_load_lds_dwordx4 v[142:143], off
	v_lshl_add_u64 v[142:143], s[24:25], 0, v[140:141]
	s_add_i32 m0, s46, 0xe000
	s_nop 0
	global_load_lds_dwordx4 v[142:143], off
	s_cmp_eq_u32 s72, 1
	s_cbranch_scc1 .Lw8_790
	s_waitcnt vmcnt(24)
	s_branch .Lwd_790

; #define PG8_STAGE(bufoff, gbase, voff) do { _Pragma("unroll") for (int _i = 0; _i < 2; ++_i) \
;         __builtin_amdgcn_global_load_lds((const unsigned*)((const char*)(gbase) + (voff)[_i]), (PG8_LAS unsigned*)(lds + (bufoff) + ldsw + _i * 8192), 16, 0, 0); } while (0)
; #define PG8_LDA(dst, b, h) do { _Pragma("unroll") for (int m = 0; m < 4; ++m) _Pragma("unroll") for (int k = 0; k < 2; ++k) dst[m][k] = *(const PG8_LAS bf16x8*)(lds + PG8_SA(b, h) + aoff + m * 2048 + k * 1024); } while (0)
; #define PG8_LDB(dst, b, h) do { _Pragma("unroll") for (int n = 0; n < 2; ++n) _Pragma("unroll") for (int k = 0; k < 2; ++k) dst[n][k] = *(const PG8_LAS bf16x8*)(lds + PG8_SB(b, h) + boff + n * 2048 + k * 1024); } while (0)
; #define PG8_WAIT_V(n) asm volatile("s_waitcnt vmcnt(" #n ")" ::: "memory")
; #define PG8_WAIT_L(n) asm volatile("s_waitcnt lgkmcnt(" #n ")" ::: "memory")
; template <class Epi, class Sched, bool ALIGN_EPI = false, bool SP2 = false, bool ABLK = false, bool BBLK = false>
; __device__ __forceinline__ void gemm_phase(PG8_LAS unsigned char* lds, const Gemm g, const Sched& S, const Epi& E) {
;     ...
;         const char* nA = has_next ? (const char*)g.A + (size_t)nxt.pm * tstepA : cA; const char* nB = has_next ? (const char*)g.Bt + (size_t)nxt.pn * tstepB : cB;
;         for (int t = 0; t < nt; t += 2) {
;             const bool last = (t == nt - 2);
;             const char* a1 = cA + (size_t)(t + 1) * kstepA;
;             const char* a2 = last ? nA : cA + (size_t)(t + 2) * kstepA; const char* b2 = last ? nB : cB + (size_t)(t + 2) * kstepB;
;             const char* a3 = a2 + kstepA; const char* b3 = b2 + kstepB;
;             if (last && has_next) S.a_ready(nxt);
;             if constexpr (SP2) {
;             PG8_LDB(B0, 0, 0); PG8_LDB(B1, 0, 1); PG8_SCHED; PG8_LDA(At, 0, 0); PG8_STAGE(PG8_SA(1, 1), a1 + hstepA, voffA);
;             PG8_WAIT_V(8); PG8_WAIT_L(0); PG8_BAR; PG8_MMA(0, 0, At, B0); PG8_MMA(0, 1, At, B1); PG8_BAR; PG8_SCHED;
;     ...
; #pragma unroll
;         for (int a = 0; a < 2; ++a)
; #pragma unroll
;             for (int b = 0; b < 2; ++b)
; #pragma unroll
;                 for (int m = 0; m < 4; ++m)
; #pragma unroll
;                     for (int n = 0; n < 2; ++n) acc[a][b][m][n] = (f32x4){0.f, 0.f, 0.f, 0.f};
;         cur = nxt; cA = nA; cB = nB; ++ui;
;         if constexpr (ALIGN_EPI) { if (wr == 1) PG8_BAR; }
.LBB0_1339:
	s_ashr_i32 s19, s18, 31
	s_lshl_b64 s[20:21], s[18:19], 20
	s_add_u32 s20, s40, s20
	s_addc_u32 s21, s41, s21
	s_and_b64 s[22:23], s[6:7], exec
	s_cselect_b32 s1, s21, s27
	s_cselect_b32 s19, s20, s26
	s_ashr_i32 s15, s14, 31
	s_lshl_b64 s[22:23], s[14:15], 20
	s_add_u32 s22, s42, s22
	s_addc_u32 s23, s43, s23
	s_and_b64 s[30:31], s[6:7], exec
	s_cselect_b32 s15, s23, s29
	s_cselect_b32 s72, s22, s28
	s_add_u32 s26, s26, 0xc000
	s_addc_u32 s27, s27, 0
	s_add_u32 s73, s28, 0x10000
	v_mov_b32_e32 v2, 0
	s_addc_u32 s81, s29, 0
	s_mov_b32 s83, -2
	s_add_u32 s28, s26, 0x4000
	s_addc_u32 s29, s27, 0
	s_cmp_eq_u32 s83, 28
	s_cselect_b32 s34, s19, s28
	s_cselect_b32 s35, s1, s29
	s_cselect_b32 s30, s72, s73
	s_cselect_b32 s31, s15, s81
	s_add_u32 s28, s34, 0x8000
	s_addc_u32 s29, s35, 0
	s_add_i32 s52, 0, 0x10000
	v_add_u32_e32 v142, s52, v145
	s_add_i32 s75, 0, 0x14000
	ds_read_b128 v[148:151], v142
	v_pk_mov_b32 v[2:3], 0, 0
	v_pk_mov_b32 v[4:5], 0, 0
	v_pk_mov_b32 v[6:7], 0, 0
	v_pk_mov_b32 v[8:9], 0, 0
	ds_read_b128 v[152:155], v142 offset:1024
	v_pk_mov_b32 v[10:11], 0, 0
	v_pk_mov_b32 v[12:13], 0, 0
	v_pk_mov_b32 v[14:15], 0, 0
	v_pk_mov_b32 v[16:17], 0, 0
	ds_read_b128 v[156:159], v142 offset:2048
	v_pk_mov_b32 v[18:19], 0, 0
	v_pk_mov_b32 v[20:21], 0, 0
	v_pk_mov_b32 v[22:23], 0, 0
	v_pk_mov_b32 v[24:25], 0, 0
	ds_read_b128 v[160:163], v142 offset:3072
	v_pk_mov_b32 v[26:27], 0, 0
	v_pk_mov_b32 v[28:29], 0, 0
	v_pk_mov_b32 v[30:31], 0, 0
	v_pk_mov_b32 v[32:33], 0, 0
	v_add_u32_e32 v142, s75, v145
	ds_read_b128 v[164:167], v142
	v_pk_mov_b32 v[34:35], 0, 0
	v_pk_mov_b32 v[36:37], 0, 0
	v_pk_mov_b32 v[38:39], 0, 0
	v_pk_mov_b32 v[40:41], 0, 0
	ds_read_b128 v[168:171], v142 offset:1024
	v_pk_mov_b32 v[42:43], 0, 0
	v_pk_mov_b32 v[44:45], 0, 0
	v_pk_mov_b32 v[46:47], 0, 0
	v_pk_mov_b32 v[48:49], 0, 0
	ds_read_b128 v[172:175], v142 offset:2048
	v_pk_mov_b32 v[50:51], 0, 0
	v_pk_mov_b32 v[52:53], 0, 0
	v_pk_mov_b32 v[54:55], 0, 0
	v_pk_mov_b32 v[56:57], 0, 0
	ds_read_b128 v[176:179], v142 offset:3072
	v_pk_mov_b32 v[58:59], 0, 0
	v_pk_mov_b32 v[60:61], 0, 0
	v_pk_mov_b32 v[62:63], 0, 0
	v_pk_mov_b32 v[64:65], 0, 0
	v_lshl_add_u64 v[142:143], s[26:27], 0, v[138:139]
	s_add_i32 m0, s25, 0xc000
	ds_read_b128 v[180:183], v146
	v_pk_mov_b32 v[66:67], 0, 0
	v_pk_mov_b32 v[68:69], 0, 0
	v_pk_mov_b32 v[70:71], 0, 0
	v_pk_mov_b32 v[72:73], 0, 0
	ds_read_b128 v[196:199], v146 offset:1024
	v_pk_mov_b32 v[74:75], 0, 0
	v_pk_mov_b32 v[76:77], 0, 0
	v_pk_mov_b32 v[78:79], 0, 0
	v_pk_mov_b32 v[80:81], 0, 0
	ds_read_b128 v[200:203], v146 offset:2048
	v_pk_mov_b32 v[82:83], 0, 0
	v_pk_mov_b32 v[84:85], 0, 0
	v_pk_mov_b32 v[86:87], 0, 0
	v_pk_mov_b32 v[88:89], 0, 0
	ds_read_b128 v[204:207], v146 offset:3072
	v_pk_mov_b32 v[90:91], 0, 0
	v_pk_mov_b32 v[92:93], 0, 0
	v_pk_mov_b32 v[94:95], 0, 0
	v_pk_mov_b32 v[96:97], 0, 0
	ds_read_b128 v[208:211], v146 offset:4096
	v_pk_mov_b32 v[98:99], 0, 0
	v_pk_mov_b32 v[100:101], 0, 0
	v_pk_mov_b32 v[102:103], 0, 0
	v_pk_mov_b32 v[104:105], 0, 0
	ds_read_b128 v[212:215], v146 offset:5120
	v_pk_mov_b32 v[106:107], 0, 0
	v_pk_mov_b32 v[108:109], 0, 0
	v_pk_mov_b32 v[110:111], 0, 0
	v_pk_mov_b32 v[112:113], 0, 0
	ds_read_b128 v[216:219], v146 offset:6144
	v_pk_mov_b32 v[114:115], 0, 0
	v_pk_mov_b32 v[116:117], 0, 0
	v_pk_mov_b32 v[118:119], 0, 0
	v_pk_mov_b32 v[120:121], 0, 0
	ds_read_b128 v[220:223], v146 offset:7168
	v_pk_mov_b32 v[122:123], 0, 0
	v_pk_mov_b32 v[124:125], 0, 0
	v_pk_mov_b32 v[126:127], 0, 0
	v_pk_mov_b32 v[128:129], 0, 0
	global_load_lds_dwordx4 v[142:143], off
	v_lshl_add_u64 v[142:143], s[26:27], 0, v[140:141]
	s_add_i32 m0, s25, 0xe000
	s_nop 0
	global_load_lds_dwordx4 v[142:143], off
	s_cmp_eq_u32 s68, 1
	s_cbranch_scc1 .Lw8_1340
	s_waitcnt vmcnt(16)
	s_branch .Lwd_1340

; #define PG8_STAGE(bufoff, gbase, voff) do { _Pragma("unroll") for (int _i = 0; _i < 2; ++_i) \
;         __builtin_amdgcn_global_load_lds((const unsigned*)((const char*)(gbase) + (voff)[_i]), (PG8_LAS unsigned*)(lds + (bufoff) + ldsw + _i * 8192), 16, 0, 0); } while (0)
; #define PG8_LDA(dst, b, h) do { _Pragma("unroll") for (int m = 0; m < 4; ++m) _Pragma("unroll") for (int k = 0; k < 2; ++k) dst[m][k] = *(const PG8_LAS bf16x8*)(lds + PG8_SA(b, h) + aoff + m * 2048 + k * 1024); } while (0)
; #define PG8_LDB(dst, b, h) do { _Pragma("unroll") for (int n = 0; n < 2; ++n) _Pragma("unroll") for (int k = 0; k < 2; ++k) dst[n][k] = *(const PG8_LAS bf16x8*)(lds + PG8_SB(b, h) + boff + n * 2048 + k * 1024); } while (0)
; #define PG8_WAIT_V(n) asm volatile("s_waitcnt vmcnt(" #n ")" ::: "memory")
; #define PG8_WAIT_L(n) asm volatile("s_waitcnt lgkmcnt(" #n ")" ::: "memory")
; template <class Epi, class Sched, bool ALIGN_EPI = false, bool SP2 = false, bool ABLK = false, bool BBLK = false>
; __device__ __forceinline__ void gemm_phase(PG8_LAS unsigned char* lds, const Gemm g, const Sched& S, const Epi& E) {
;     ...
;         const char* nA = has_next ? (const char*)g.A + (size_t)nxt.pm * tstepA : cA; const char* nB = has_next ? (const char*)g.Bt + (size_t)nxt.pn * tstepB : cB;
;         for (int t = 0; t < nt; t += 2) {
;             const bool last = (t == nt - 2);
;             const char* a1 = cA + (size_t)(t + 1) * kstepA;
;             const char* a2 = last ? nA : cA + (size_t)(t + 2) * kstepA; const char* b2 = last ? nB : cB + (size_t)(t + 2) * kstepB;
;             const char* a3 = a2 + kstepA; const char* b3 = b2 + kstepB;
;             if (last && has_next) S.a_ready(nxt);
;             if constexpr (SP2) {
;             PG8_LDB(B0, 0, 0); PG8_LDB(B1, 0, 1); PG8_SCHED; PG8_LDA(At, 0, 0); PG8_STAGE(PG8_SA(1, 1), a1 + hstepA, voffA);
;             PG8_WAIT_V(8); PG8_WAIT_L(0); PG8_BAR; PG8_MMA(0, 0, At, B0); PG8_MMA(0, 1, At, B1); PG8_BAR; PG8_SCHED;
;     ...
; #pragma unroll
;         for (int a = 0; a < 2; ++a)
; #pragma unroll
;             for (int b = 0; b < 2; ++b)
; #pragma unroll
;                 for (int m = 0; m < 4; ++m)
; #pragma unroll
;                     for (int n = 0; n < 2; ++n) acc[a][b][m][n] = (f32x4){0.f, 0.f, 0.f, 0.f};
;         cur = nxt; cA = nA; cB = nB; ++ui;
;         if constexpr (ALIGN_EPI) { if (wr == 1) PG8_BAR; }
.LBB0_1419:
	s_add_u32 s0, s0, 0xc000
	s_addc_u32 s1, s1, 0
	s_add_u32 s23, s26, 0x10000
	v_mov_b32_e32 v2, 0
	s_addc_u32 s25, s27, 0
	s_mov_b32 s73, -2
	s_add_u32 s8, s0, 0x4000
	s_addc_u32 s9, s1, 0
	s_cmpk_eq_i32 s73, 0x54
	s_cselect_b32 s28, s18, s8
	s_cselect_b32 s29, s19, s9
	s_cselect_b32 s26, s20, s23
	s_cselect_b32 s27, s21, s25
	s_add_u32 s8, s28, 0x8000
	s_addc_u32 s9, s29, 0
	s_add_i32 s52, 0, 0x10000
	s_add_i32 s75, 0, 0x14000
	v_add_u32_e32 v142, s52, v180
	v_add_u32_e32 v168, s75, v180
	ds_read_b128 v[130:133], v142
	v_pk_mov_b32 v[2:3], 0, 0
	v_pk_mov_b32 v[4:5], 0, 0
	v_pk_mov_b32 v[6:7], 0, 0
	v_pk_mov_b32 v[8:9], 0, 0
	ds_read_b128 v[134:137], v142 offset:1024
	v_pk_mov_b32 v[10:11], 0, 0
	v_pk_mov_b32 v[12:13], 0, 0
	v_pk_mov_b32 v[14:15], 0, 0
	v_pk_mov_b32 v[16:17], 0, 0
	ds_read_b128 v[138:141], v142 offset:2048
	v_pk_mov_b32 v[18:19], 0, 0
	v_pk_mov_b32 v[20:21], 0, 0
	v_pk_mov_b32 v[22:23], 0, 0
	v_pk_mov_b32 v[24:25], 0, 0
	ds_read_b128 v[142:145], v142 offset:3072
	v_pk_mov_b32 v[26:27], 0, 0
	v_pk_mov_b32 v[28:29], 0, 0
	v_pk_mov_b32 v[30:31], 0, 0
	v_pk_mov_b32 v[32:33], 0, 0
	ds_read_b128 v[156:159], v168
	v_pk_mov_b32 v[34:35], 0, 0
	v_pk_mov_b32 v[36:37], 0, 0
	v_pk_mov_b32 v[38:39], 0, 0
	v_pk_mov_b32 v[40:41], 0, 0
	ds_read_b128 v[160:163], v168 offset:1024
	v_pk_mov_b32 v[42:43], 0, 0
	v_pk_mov_b32 v[44:45], 0, 0
	v_pk_mov_b32 v[46:47], 0, 0
	v_pk_mov_b32 v[48:49], 0, 0
	ds_read_b128 v[164:167], v168 offset:2048
	v_pk_mov_b32 v[50:51], 0, 0
	v_pk_mov_b32 v[52:53], 0, 0
	v_pk_mov_b32 v[54:55], 0, 0
	v_pk_mov_b32 v[56:57], 0, 0
	ds_read_b128 v[168:171], v168 offset:3072
	v_pk_mov_b32 v[58:59], 0, 0
	v_pk_mov_b32 v[60:61], 0, 0
	v_pk_mov_b32 v[62:63], 0, 0
	v_pk_mov_b32 v[64:65], 0, 0
	v_lshl_add_u64 v[176:177], s[0:1], 0, v[152:153]
	s_add_i32 m0, s3, 0xc000
	ds_read_b128 v[172:175], v181
	v_pk_mov_b32 v[66:67], 0, 0
	v_pk_mov_b32 v[68:69], 0, 0
	v_pk_mov_b32 v[70:71], 0, 0
	v_pk_mov_b32 v[72:73], 0, 0
	ds_read_b128 v[182:185], v181 offset:1024
	v_pk_mov_b32 v[74:75], 0, 0
	v_pk_mov_b32 v[76:77], 0, 0
	v_pk_mov_b32 v[78:79], 0, 0
	v_pk_mov_b32 v[80:81], 0, 0
	ds_read_b128 v[196:199], v181 offset:2048
	v_pk_mov_b32 v[82:83], 0, 0
	v_pk_mov_b32 v[84:85], 0, 0
	v_pk_mov_b32 v[86:87], 0, 0
	v_pk_mov_b32 v[88:89], 0, 0
	ds_read_b128 v[200:203], v181 offset:3072
	v_pk_mov_b32 v[90:91], 0, 0
	v_pk_mov_b32 v[92:93], 0, 0
	v_pk_mov_b32 v[94:95], 0, 0
	v_pk_mov_b32 v[96:97], 0, 0
	ds_read_b128 v[204:207], v181 offset:4096
	v_pk_mov_b32 v[98:99], 0, 0
	v_pk_mov_b32 v[100:101], 0, 0
	v_pk_mov_b32 v[102:103], 0, 0
	v_pk_mov_b32 v[104:105], 0, 0
	ds_read_b128 v[208:211], v181 offset:5120
	v_pk_mov_b32 v[106:107], 0, 0
	v_pk_mov_b32 v[108:109], 0, 0
	v_pk_mov_b32 v[110:111], 0, 0
	v_pk_mov_b32 v[112:113], 0, 0
	ds_read_b128 v[212:215], v181 offset:6144
	v_pk_mov_b32 v[114:115], 0, 0
	v_pk_mov_b32 v[116:117], 0, 0
	v_pk_mov_b32 v[118:119], 0, 0
	v_pk_mov_b32 v[120:121], 0, 0
	ds_read_b128 v[216:219], v181 offset:7168
	v_pk_mov_b32 v[122:123], 0, 0
	v_pk_mov_b32 v[124:125], 0, 0
	v_pk_mov_b32 v[126:127], 0, 0
	v_pk_mov_b32 v[128:129], 0, 0
	global_load_lds_dwordx4 v[176:177], off
	v_lshl_add_u64 v[176:177], s[0:1], 0, v[154:155]
	s_add_i32 m0, s3, 0xe000
	s_nop 0
	global_load_lds_dwordx4 v[176:177], off
	s_cmp_eq_u32 s65, 1
	s_cbranch_scc1 .Lw8_1420
	s_waitcnt vmcnt(24)
	s_branch .Lwd_1420
